# initial modulation phase (LN -1): the four modulation pieces of each row loaded together, 12 of 16 waits removed
# speedup vs baseline: 1.0121x; 1.0074x over previous
.LBB0_27:
	v_add_u32_e32 v1, s38, v32
	v_add_u32_e32 v2, s35, v32
	v_cmp_lt_i32_e32 vcc, s6, v1
	v_add_u32_e32 v0, 0xfffff000, v32
	v_add_u32_e32 v3, s33, v32
	v_cndmask_b32_e32 v88, v1, v32, vcc
	v_cmp_lt_i32_e32 vcc, s6, v2
	v_ashrrev_i32_e32 v4, 10, v0
	v_add_u32_e32 v1, 1, v4
	v_cndmask_b32_e32 v46, v2, v32, vcc
	v_cmp_lt_i32_e32 vcc, s6, v3
	v_add_u32_e32 v6, 0xfffff000, v88
	v_ashrrev_i32_e32 v5, 10, v6
	v_cndmask_b32_e32 v44, v3, v32, vcc
	v_cmp_gt_i32_e32 vcc, s2, v32
	s_waitcnt lgkmcnt(0)
	v_mov_b32_e32 v12, s87
	v_mov_b32_e32 v13, s85
	v_cndmask_b32_e64 v4, v1, 0, vcc
	v_mov_b32_e32 v14, s86
	v_mov_b32_e32 v15, s84
	v_cndmask_b32_e32 v1, 0, v33, vcc
	v_cndmask_b32_e32 v0, v0, v32, vcc
	v_add_u32_e32 v10, 1, v5
	v_mul_hi_i32_i24_e32 v5, 0x9000, v4
	v_mul_i32_i24_e32 v4, 0x9000, v4
	v_cndmask_b32_e32 v3, v12, v13, vcc
	v_cndmask_b32_e32 v2, v14, v15, vcc
	v_lshlrev_b64 v[0:1], 12, v[0:1]
	v_lshl_add_u64 v[4:5], s[60:61], 0, v[4:5]
	v_lshl_add_u64 v[0:1], v[2:3], 0, v[0:1]
	v_lshl_add_u64 v[90:91], v[4:5], 0, s[30:31]
	v_lshl_add_u64 v[92:93], v[4:5], 0, v[152:153]
	v_lshl_add_u64 v[0:1], v[0:1], 0, v[152:153]
	v_lshl_add_u64 v[4:5], v[90:91], 0, v[152:153]
	global_load_dwordx4 v[154:157], v[92:93], off offset:1024
	global_load_dwordx4 v[158:161], v[92:93], off offset:2048
	global_load_dwordx4 v[162:165], v[92:93], off offset:3072
	flat_load_dwordx4 v[48:51], v[92:93]
	global_load_dwordx4 v[166:169], v[4:5], off offset:1024
	global_load_dwordx4 v[170:173], v[4:5], off offset:2048
	global_load_dwordx4 v[174:177], v[4:5], off offset:3072
	flat_load_dwordx4 v[52:55], v[4:5]
	global_load_dwordx4 v[56:59], v[0:1], off
	v_add_u32_e32 v16, 0xfffff000, v44
	v_add_u32_e32 v8, 0xfffff000, v46
	v_ashrrev_i32_e32 v9, 10, v16
	v_ashrrev_i32_e32 v89, 31, v88
	v_ashrrev_i32_e32 v47, 31, v46
	v_ashrrev_i32_e32 v7, 10, v8
	v_cmp_gt_i32_e32 vcc, s2, v46
	v_add_u32_e32 v9, 1, v9
	v_cmp_gt_i32_e64 s[8:9], s2, v44
	v_cmp_gt_i32_e64 s[10:11], s2, v88
	v_ashrrev_i32_e32 v45, 31, v44
	v_add_u32_e32 v7, 1, v7
	v_cndmask_b32_e64 v100, v9, 0, s[8:9]
	v_cndmask_b32_e64 v3, 0, v89, s[10:11]
	v_cndmask_b32_e64 v2, v6, v88, s[10:11]
	v_cndmask_b32_e32 v9, 0, v47, vcc
	v_cndmask_b32_e32 v8, v8, v46, vcc
	v_cndmask_b32_e64 v98, v10, 0, s[10:11]
	v_cndmask_b32_e64 v99, v7, 0, vcc
	v_cndmask_b32_e64 v7, v12, v13, s[10:11]
	v_cndmask_b32_e64 v6, v14, v15, s[10:11]
	v_cndmask_b32_e32 v11, v12, v13, vcc
	v_cndmask_b32_e32 v10, v14, v15, vcc
	v_cndmask_b32_e64 v5, 0, v45, s[8:9]
	v_cndmask_b32_e64 v4, v16, v44, s[8:9]
	v_lshlrev_b64 v[2:3], 12, v[2:3]
	v_lshlrev_b64 v[8:9], 12, v[8:9]
	v_cndmask_b32_e64 v13, v12, v13, s[8:9]
	v_cndmask_b32_e64 v12, v14, v15, s[8:9]
	v_lshlrev_b64 v[4:5], 12, v[4:5]
	global_load_dwordx4 v[60:63], v[0:1], off offset:1024
	global_load_dwordx4 v[64:67], v[0:1], off offset:2048
	global_load_dwordx4 v[68:71], v[0:1], off offset:3072
	v_lshl_add_u64 v[0:1], v[6:7], 0, v[2:3]
	v_lshl_add_u64 v[2:3], v[10:11], 0, v[8:9]
	v_mov_b32_e32 v39, v153
	v_lshl_add_u64 v[4:5], v[12:13], 0, v[4:5]
	v_lshl_add_u64 v[0:1], v[0:1], 0, v[152:153]
	v_lshl_add_u64 v[2:3], v[2:3], 0, v[152:153]
	v_lshl_add_u64 v[94:95], v[90:91], 0, v[38:39]
	v_lshl_add_u64 v[96:97], v[4:5], 0, v[152:153]
	global_load_dwordx4 v[72:75], v[0:1], off
	global_load_dwordx4 v[76:79], v[0:1], off offset:1024
	global_load_dwordx4 v[80:83], v[0:1], off offset:2048
	global_load_dwordx4 v[84:87], v[0:1], off offset:3072
	global_load_dwordx4 v[28:31], v[2:3], off
	global_load_dwordx4 v[24:27], v[2:3], off offset:1024
	global_load_dwordx4 v[20:23], v[2:3], off offset:2048
	global_load_dwordx4 v[16:19], v[2:3], off offset:3072
	global_load_dwordx4 v[12:15], v[96:97], off
	global_load_dwordx4 v[8:11], v[96:97], off offset:1024
	global_load_dwordx4 v[4:7], v[96:97], off offset:2048
	s_nop 0
	global_load_dwordx4 v[0:3], v[96:97], off offset:3072
	v_mov_b32_e32 v41, v153
	v_mov_b32_e32 v43, v153
	v_lshlrev_b64 v[46:47], 11, v[46:47]
	v_lshl_add_u64 v[32:33], v[32:33], 0, s[96:97]
	v_cmp_lt_i32_e32 vcc, s6, v32
	s_or_b64 s[16:17], vcc, s[16:17]
	s_waitcnt vmcnt(0) lgkmcnt(0)
	v_pk_add_f32 v[54:55], v[54:55], 1.0 op_sel_hi:[1,0]
	v_pk_add_f32 v[52:53], v[52:53], 1.0 op_sel_hi:[1,0]
	v_pk_fma_f32 v[50:51], v[58:59], v[54:55], v[50:51]
	v_pk_fma_f32 v[48:49], v[56:57], v[52:53], v[48:49]
	v_lshl_add_u64 v[56:57], v[90:91], 0, v[40:41]
	v_cvt_pk_bf16_f32 v48, v48, v49
	v_cvt_pk_bf16_f32 v49, v50, v51
	flat_store_dwordx2 v[36:37], v[48:49]
	v_mov_b64_e32 v[48:49], v[166:167]
	v_mov_b64_e32 v[50:51], v[168:169]
	s_nop 0
	v_mov_b64_e32 v[52:53], v[154:155]
	v_mov_b64_e32 v[54:55], v[156:157]
	v_pk_add_f32 v[50:51], v[50:51], 1.0 op_sel_hi:[1,0]
	v_pk_add_f32 v[48:49], v[48:49], 1.0 op_sel_hi:[1,0]
	v_pk_fma_f32 v[50:51], v[62:63], v[50:51], v[54:55]
	v_pk_fma_f32 v[48:49], v[60:61], v[48:49], v[52:53]
	s_nop 0
	v_cvt_pk_bf16_f32 v48, v48, v49
	v_cvt_pk_bf16_f32 v49, v50, v51
	flat_store_dwordx2 v[36:37], v[48:49] offset:512
	v_mov_b64_e32 v[48:49], v[170:171]
	v_mov_b64_e32 v[50:51], v[172:173]
	s_nop 0
	v_mov_b64_e32 v[52:53], v[158:159]
	v_mov_b64_e32 v[54:55], v[160:161]
	v_lshl_add_u64 v[56:57], v[90:91], 0, v[42:43]
	v_pk_add_f32 v[50:51], v[50:51], 1.0 op_sel_hi:[1,0]
	v_pk_add_f32 v[48:49], v[48:49], 1.0 op_sel_hi:[1,0]
	v_pk_fma_f32 v[50:51], v[66:67], v[50:51], v[54:55]
	v_pk_fma_f32 v[48:49], v[64:65], v[48:49], v[52:53]
	s_nop 0
	v_cvt_pk_bf16_f32 v48, v48, v49
	v_cvt_pk_bf16_f32 v49, v50, v51
	flat_store_dwordx2 v[36:37], v[48:49] offset:1024
	v_mov_b64_e32 v[48:49], v[174:175]
	v_mov_b64_e32 v[50:51], v[176:177]
	s_nop 0
	v_mov_b64_e32 v[52:53], v[162:163]
	v_mov_b64_e32 v[54:55], v[164:165]
	v_mul_hi_i32_i24_e32 v57, 0x9000, v98
	v_mul_i32_i24_e32 v56, 0x9000, v98
	v_lshl_add_u64 v[56:57], s[60:61], 0, v[56:57]
	v_lshl_add_u64 v[58:59], v[56:57], 0, s[30:31]
	v_lshl_add_u64 v[60:61], v[58:59], 0, v[152:153]
	v_lshl_add_u64 v[56:57], v[56:57], 0, v[152:153]
	v_lshl_add_u64 v[62:63], v[58:59], 0, v[38:39]
	v_pk_add_f32 v[50:51], v[50:51], 1.0 op_sel_hi:[1,0]
	v_pk_add_f32 v[48:49], v[48:49], 1.0 op_sel_hi:[1,0]
	v_pk_fma_f32 v[50:51], v[70:71], v[50:51], v[54:55]
	v_pk_fma_f32 v[48:49], v[68:69], v[48:49], v[52:53]
	s_nop 0
	v_cvt_pk_bf16_f32 v48, v48, v49
	v_cvt_pk_bf16_f32 v49, v50, v51
	flat_store_dwordx2 v[36:37], v[48:49] offset:1536
	global_load_dwordx4 v[154:157], v[60:61], off offset:1024
	global_load_dwordx4 v[158:161], v[60:61], off offset:2048
	global_load_dwordx4 v[162:165], v[60:61], off offset:3072
	flat_load_dwordx4 v[48:51], v[60:61]
	s_nop 0
	global_load_dwordx4 v[166:169], v[56:57], off offset:1024
	global_load_dwordx4 v[170:173], v[56:57], off offset:2048
	global_load_dwordx4 v[174:177], v[56:57], off offset:3072
	flat_load_dwordx4 v[52:55], v[56:57]
	v_lshlrev_b64 v[60:61], 11, v[88:89]
	v_lshl_add_u64 v[60:61], v[34:35], 0, v[60:61]
	v_lshl_add_u64 v[36:37], v[36:37], 0, s[22:23]
	s_waitcnt vmcnt(0) lgkmcnt(0)
	v_pk_add_f32 v[50:51], v[50:51], 1.0 op_sel_hi:[1,0]
	v_pk_add_f32 v[48:49], v[48:49], 1.0 op_sel_hi:[1,0]
	v_pk_fma_f32 v[50:51], v[74:75], v[50:51], v[54:55]
	v_pk_fma_f32 v[48:49], v[72:73], v[48:49], v[52:53]
	s_nop 0
	v_cvt_pk_bf16_f32 v48, v48, v49
	v_cvt_pk_bf16_f32 v49, v50, v51
	flat_store_dwordx2 v[60:61], v[48:49]
	v_mov_b64_e32 v[48:49], v[154:155]
	v_mov_b64_e32 v[50:51], v[156:157]
	s_nop 0
	v_mov_b64_e32 v[52:53], v[166:167]
	v_mov_b64_e32 v[54:55], v[168:169]
	v_lshl_add_u64 v[62:63], v[58:59], 0, v[40:41]
	v_lshl_add_u64 v[58:59], v[58:59], 0, v[42:43]
	v_pk_add_f32 v[50:51], v[50:51], 1.0 op_sel_hi:[1,0]
	v_pk_add_f32 v[48:49], v[48:49], 1.0 op_sel_hi:[1,0]
	v_pk_fma_f32 v[50:51], v[78:79], v[50:51], v[54:55]
	v_pk_fma_f32 v[48:49], v[76:77], v[48:49], v[52:53]
	s_nop 0
	v_cvt_pk_bf16_f32 v48, v48, v49
	v_cvt_pk_bf16_f32 v49, v50, v51
	flat_store_dwordx2 v[60:61], v[48:49] offset:512
	v_mov_b64_e32 v[48:49], v[158:159]
	v_mov_b64_e32 v[50:51], v[160:161]
	s_nop 0
	v_mov_b64_e32 v[52:53], v[170:171]
	v_mov_b64_e32 v[54:55], v[172:173]
	v_pk_add_f32 v[50:51], v[50:51], 1.0 op_sel_hi:[1,0]
	v_pk_add_f32 v[48:49], v[48:49], 1.0 op_sel_hi:[1,0]
	v_pk_fma_f32 v[50:51], v[82:83], v[50:51], v[54:55]
	v_pk_fma_f32 v[48:49], v[80:81], v[48:49], v[52:53]
	s_nop 0
	v_cvt_pk_bf16_f32 v48, v48, v49
	v_cvt_pk_bf16_f32 v49, v50, v51
	flat_store_dwordx2 v[60:61], v[48:49] offset:1024
	v_mov_b64_e32 v[48:49], v[162:163]
	v_mov_b64_e32 v[50:51], v[164:165]
	s_nop 0
	v_mov_b64_e32 v[52:53], v[174:175]
	v_mov_b64_e32 v[54:55], v[176:177]
	v_mul_hi_i32_i24_e32 v57, 0x9000, v99
	v_mul_i32_i24_e32 v56, 0x9000, v99
	v_lshl_add_u64 v[56:57], s[60:61], 0, v[56:57]
	v_lshl_add_u64 v[58:59], v[56:57], 0, s[30:31]
	v_lshl_add_u64 v[62:63], v[58:59], 0, v[152:153]
	v_lshl_add_u64 v[56:57], v[56:57], 0, v[152:153]
	v_pk_add_f32 v[50:51], v[50:51], 1.0 op_sel_hi:[1,0]
	v_pk_add_f32 v[48:49], v[48:49], 1.0 op_sel_hi:[1,0]
	v_pk_fma_f32 v[50:51], v[86:87], v[50:51], v[54:55]
	v_pk_fma_f32 v[48:49], v[84:85], v[48:49], v[52:53]
	s_nop 0
	v_cvt_pk_bf16_f32 v48, v48, v49
	v_cvt_pk_bf16_f32 v49, v50, v51
	flat_store_dwordx2 v[60:61], v[48:49] offset:1536
	global_load_dwordx4 v[154:157], v[62:63], off offset:1024
	global_load_dwordx4 v[158:161], v[62:63], off offset:2048
	global_load_dwordx4 v[162:165], v[62:63], off offset:3072
	flat_load_dwordx4 v[48:51], v[62:63]
	s_nop 0
	global_load_dwordx4 v[166:169], v[56:57], off offset:1024
	global_load_dwordx4 v[170:173], v[56:57], off offset:2048
	global_load_dwordx4 v[174:177], v[56:57], off offset:3072
	flat_load_dwordx4 v[52:55], v[56:57]
	v_lshl_add_u64 v[60:61], v[34:35], 0, v[46:47]
	v_lshl_add_u64 v[46:47], v[58:59], 0, v[38:39]
	s_waitcnt vmcnt(0) lgkmcnt(0)
	v_pk_add_f32 v[50:51], v[50:51], 1.0 op_sel_hi:[1,0]
	v_pk_add_f32 v[48:49], v[48:49], 1.0 op_sel_hi:[1,0]
	v_pk_fma_f32 v[30:31], v[30:31], v[50:51], v[54:55]
	v_pk_fma_f32 v[28:29], v[28:29], v[48:49], v[52:53]
	v_lshl_add_u64 v[50:51], v[58:59], 0, v[40:41]
	v_cvt_pk_bf16_f32 v28, v28, v29
	v_cvt_pk_bf16_f32 v29, v30, v31
	flat_store_dwordx2 v[60:61], v[28:29]
	v_mov_b64_e32 v[28:29], v[154:155]
	v_mov_b64_e32 v[30:31], v[156:157]
	s_nop 0
	v_mov_b64_e32 v[46:47], v[166:167]
	v_mov_b64_e32 v[48:49], v[168:169]
	v_pk_add_f32 v[30:31], v[30:31], 1.0 op_sel_hi:[1,0]
	v_pk_add_f32 v[28:29], v[28:29], 1.0 op_sel_hi:[1,0]
	v_pk_fma_f32 v[26:27], v[26:27], v[30:31], v[48:49]
	v_pk_fma_f32 v[24:25], v[24:25], v[28:29], v[46:47]
	v_lshl_add_u64 v[46:47], v[58:59], 0, v[42:43]
	v_cvt_pk_bf16_f32 v24, v24, v25
	v_cvt_pk_bf16_f32 v25, v26, v27
	flat_store_dwordx2 v[60:61], v[24:25] offset:512
	v_mov_b64_e32 v[24:25], v[158:159]
	v_mov_b64_e32 v[26:27], v[160:161]
	s_nop 0
	v_mov_b64_e32 v[28:29], v[170:171]
	v_mov_b64_e32 v[30:31], v[172:173]
	v_pk_add_f32 v[26:27], v[26:27], 1.0 op_sel_hi:[1,0]
	v_pk_add_f32 v[24:25], v[24:25], 1.0 op_sel_hi:[1,0]
	v_pk_fma_f32 v[22:23], v[22:23], v[26:27], v[30:31]
	v_pk_fma_f32 v[20:21], v[20:21], v[24:25], v[28:29]
	v_mul_hi_i32_i24_e32 v29, 0x9000, v100
	v_cvt_pk_bf16_f32 v20, v20, v21
	v_cvt_pk_bf16_f32 v21, v22, v23
	flat_store_dwordx2 v[60:61], v[20:21] offset:1024
	v_mov_b64_e32 v[20:21], v[162:163]
	v_mov_b64_e32 v[22:23], v[164:165]
	s_nop 0
	v_mov_b64_e32 v[24:25], v[174:175]
	v_mov_b64_e32 v[26:27], v[176:177]
	v_mul_i32_i24_e32 v28, 0x9000, v100
	v_lshl_add_u64 v[28:29], s[60:61], 0, v[28:29]
	v_lshl_add_u64 v[30:31], v[28:29], 0, s[30:31]
	v_lshl_add_u64 v[46:47], v[30:31], 0, v[152:153]
	v_lshl_add_u64 v[28:29], v[28:29], 0, v[152:153]
	v_pk_add_f32 v[22:23], v[22:23], 1.0 op_sel_hi:[1,0]
	v_pk_add_f32 v[20:21], v[20:21], 1.0 op_sel_hi:[1,0]
	v_pk_fma_f32 v[18:19], v[18:19], v[22:23], v[26:27]
	v_pk_fma_f32 v[16:17], v[16:17], v[20:21], v[24:25]
	v_lshlrev_b64 v[24:25], 11, v[44:45]
	v_cvt_pk_bf16_f32 v16, v16, v17
	v_cvt_pk_bf16_f32 v17, v18, v19
	flat_store_dwordx2 v[60:61], v[16:17] offset:1536
	global_load_dwordx4 v[154:157], v[46:47], off offset:1024
	global_load_dwordx4 v[158:161], v[46:47], off offset:2048
	global_load_dwordx4 v[162:165], v[46:47], off offset:3072
	flat_load_dwordx4 v[16:19], v[46:47]
	s_nop 0
	global_load_dwordx4 v[166:169], v[28:29], off offset:1024
	global_load_dwordx4 v[170:173], v[28:29], off offset:2048
	global_load_dwordx4 v[174:177], v[28:29], off offset:3072
	flat_load_dwordx4 v[20:23], v[28:29]
	v_lshl_add_u64 v[24:25], v[34:35], 0, v[24:25]
	v_lshl_add_u64 v[26:27], v[30:31], 0, v[38:39]
	s_waitcnt vmcnt(0) lgkmcnt(0)
	v_pk_add_f32 v[18:19], v[18:19], 1.0 op_sel_hi:[1,0]
	v_pk_add_f32 v[16:17], v[16:17], 1.0 op_sel_hi:[1,0]
	v_pk_fma_f32 v[14:15], v[14:15], v[18:19], v[22:23]
	v_pk_fma_f32 v[12:13], v[12:13], v[16:17], v[20:21]
	v_lshl_add_u64 v[20:21], v[30:31], 0, v[40:41]
	v_cvt_pk_bf16_f32 v12, v12, v13
	v_cvt_pk_bf16_f32 v13, v14, v15
	flat_store_dwordx2 v[24:25], v[12:13]
	v_mov_b64_e32 v[12:13], v[154:155]
	v_mov_b64_e32 v[14:15], v[156:157]
	s_nop 0
	v_mov_b64_e32 v[16:17], v[166:167]
	v_mov_b64_e32 v[18:19], v[168:169]
	v_pk_add_f32 v[14:15], v[14:15], 1.0 op_sel_hi:[1,0]
	v_pk_add_f32 v[12:13], v[12:13], 1.0 op_sel_hi:[1,0]
	v_pk_fma_f32 v[10:11], v[10:11], v[14:15], v[18:19]
	v_pk_fma_f32 v[8:9], v[8:9], v[12:13], v[16:17]
	v_lshl_add_u64 v[16:17], v[30:31], 0, v[42:43]
	v_cvt_pk_bf16_f32 v8, v8, v9
	v_cvt_pk_bf16_f32 v9, v10, v11
	flat_store_dwordx2 v[24:25], v[8:9] offset:512
	v_mov_b64_e32 v[8:9], v[158:159]
	v_mov_b64_e32 v[10:11], v[160:161]
	s_nop 0
	v_mov_b64_e32 v[12:13], v[170:171]
	v_mov_b64_e32 v[14:15], v[172:173]
	v_pk_add_f32 v[10:11], v[10:11], 1.0 op_sel_hi:[1,0]
	v_pk_add_f32 v[8:9], v[8:9], 1.0 op_sel_hi:[1,0]
	v_pk_fma_f32 v[6:7], v[6:7], v[10:11], v[14:15]
	v_pk_fma_f32 v[4:5], v[4:5], v[8:9], v[12:13]
	s_nop 0
	v_cvt_pk_bf16_f32 v4, v4, v5
	v_cvt_pk_bf16_f32 v5, v6, v7
	flat_store_dwordx2 v[24:25], v[4:5] offset:1024
	v_mov_b64_e32 v[4:5], v[162:163]
	v_mov_b64_e32 v[6:7], v[164:165]
	s_nop 0
	v_mov_b64_e32 v[8:9], v[174:175]
	v_mov_b64_e32 v[10:11], v[176:177]
	v_pk_add_f32 v[6:7], v[6:7], 1.0 op_sel_hi:[1,0]
	v_pk_add_f32 v[4:5], v[4:5], 1.0 op_sel_hi:[1,0]
	v_pk_fma_f32 v[2:3], v[2:3], v[6:7], v[10:11]
	v_pk_fma_f32 v[0:1], v[0:1], v[4:5], v[8:9]
	s_nop 0
	v_cvt_pk_bf16_f32 v0, v0, v1
	v_cvt_pk_bf16_f32 v1, v2, v3
	flat_store_dwordx2 v[24:25], v[0:1] offset:1536
	s_andn2_b64 exec, exec, s[16:17]
	s_cbranch_execnz .LBB0_27
